# combined variant + kernel-start read of the kernel's own code range into L2 (instruction prefetch)
# baseline (speedup 1.0000x reference)
_Z8mega_fwd4Args:
	s_load_dwordx16 s[4:19], s[0:1], 0x80
	s_getpc_b64 s[100:101]
.Lcodepf_here:
	v_and_b32_e32 v100, 0x3ff, v0
	v_lshlrev_b32_e32 v100, 4, v100
	s_mov_b32 vcc_lo, (.Lcodepf_end-.Lcodepf_here-16)&4294967295
	v_min_u32_e32 v101, vcc_lo, v100
	global_load_dwordx4 v[104:107], v101, s[100:101]
	v_add_u32_e32 v100, 0x2000, v100
	v_min_u32_e32 v101, vcc_lo, v100
	global_load_dwordx4 v[104:107], v101, s[100:101]
	v_add_u32_e32 v100, 0x2000, v100
	v_min_u32_e32 v101, vcc_lo, v100
	global_load_dwordx4 v[104:107], v101, s[100:101]
	v_add_u32_e32 v100, 0x2000, v100
	v_min_u32_e32 v101, vcc_lo, v100
	global_load_dwordx4 v[104:107], v101, s[100:101]
	v_add_u32_e32 v100, 0x2000, v100
	v_min_u32_e32 v101, vcc_lo, v100
	global_load_dwordx4 v[104:107], v101, s[100:101]
	v_add_u32_e32 v100, 0x2000, v100
	v_min_u32_e32 v101, vcc_lo, v100
	global_load_dwordx4 v[104:107], v101, s[100:101]
	v_add_u32_e32 v100, 0x2000, v100
	v_min_u32_e32 v101, vcc_lo, v100
	global_load_dwordx4 v[104:107], v101, s[100:101]
	v_add_u32_e32 v100, 0x2000, v100
	v_min_u32_e32 v101, vcc_lo, v100
	global_load_dwordx4 v[104:107], v101, s[100:101]
	v_add_u32_e32 v100, 0x2000, v100
	v_min_u32_e32 v101, vcc_lo, v100
	global_load_dwordx4 v[104:107], v101, s[100:101]
	v_add_u32_e32 v100, 0x2000, v100
	v_min_u32_e32 v101, vcc_lo, v100
	global_load_dwordx4 v[104:107], v101, s[100:101]
	v_add_u32_e32 v100, 0x2000, v100
	v_min_u32_e32 v101, vcc_lo, v100
	global_load_dwordx4 v[104:107], v101, s[100:101]
	v_add_u32_e32 v100, 0x2000, v100
	v_min_u32_e32 v101, vcc_lo, v100
	global_load_dwordx4 v[104:107], v101, s[100:101]
	v_add_u32_e32 v100, 0x2000, v100
	v_min_u32_e32 v101, vcc_lo, v100
	global_load_dwordx4 v[104:107], v101, s[100:101]
	v_add_u32_e32 v100, 0x2000, v100
	v_min_u32_e32 v101, vcc_lo, v100
	global_load_dwordx4 v[104:107], v101, s[100:101]
	v_add_u32_e32 v100, 0x2000, v100
	v_min_u32_e32 v101, vcc_lo, v100
	global_load_dwordx4 v[104:107], v101, s[100:101]
	v_add_u32_e32 v100, 0x2000, v100
	v_min_u32_e32 v101, vcc_lo, v100
	global_load_dwordx4 v[104:107], v101, s[100:101]
	v_add_u32_e32 v100, 0x2000, v100
	v_min_u32_e32 v101, vcc_lo, v100
	global_load_dwordx4 v[104:107], v101, s[100:101]
	s_waitcnt vmcnt(0)
	s_load_dwordx4 s[88:91], s[0:1], 0xc0
	v_writelane_b32 v251, s2, 0
	s_add_u32 s2, s0, 0xc8
	s_addc_u32 s3, s1, 0
	s_waitcnt lgkmcnt(0)
	v_writelane_b32 v251, s4, 1
	v_and_b32_e32 v183, 0x3ff, v0
	v_cmp_gt_u32_e32 vcc, 4, v183
	v_writelane_b32 v251, s5, 2
	v_writelane_b32 v251, s6, 3
	v_writelane_b32 v251, s7, 4
	v_writelane_b32 v251, s8, 5
	v_writelane_b32 v251, s9, 6
	v_writelane_b32 v251, s10, 7
	v_writelane_b32 v251, s11, 8
	v_writelane_b32 v251, s12, 9
	v_writelane_b32 v251, s13, 10
	v_writelane_b32 v251, s14, 11
	v_writelane_b32 v251, s15, 12
	v_writelane_b32 v251, s16, 13
	v_writelane_b32 v251, s17, 14
	v_writelane_b32 v251, s18, 15
	v_writelane_b32 v251, s19, 16
	v_writelane_b32 v251, s2, 17
	s_nop 1
	v_writelane_b32 v251, s3, 18
	s_and_saveexec_b64 s[2:3], vcc
	v_lshl_add_u32 v1, v183, 2, 0
	v_add_u32_e32 v1, 0x22000, v1
	v_mov_b32_e32 v2, 0
	ds_write_b32 v1, v2
	s_or_b64 exec, exec, s[2:3]
	s_load_dwordx16 s[4:19], s[0:1], 0x80
	s_waitcnt lgkmcnt(0)
	s_barrier
	s_getreg_b32 s4, hwreg(HW_REG_XCC_ID, 0, 4)
	s_add_u32 s2, s18, 0x1e700000
	s_addc_u32 s3, s19, 0
	s_and_b32 s8, s4, 15
	v_cmp_eq_u32_e64 s[6:7], 0, v183
	s_mov_b64 s[4:5], exec
	s_nop 0
	v_writelane_b32 v251, s6, 19
	s_nop 1
	v_writelane_b32 v251, s7, 20
	s_and_b64 s[6:7], s[4:5], s[6:7]
	s_mov_b64 exec, s[6:7]
	s_cbranch_execz .LBB0_5
	s_mov_b64 s[6:7], exec
	v_mbcnt_lo_u32_b32 v1, s6, 0
	v_mbcnt_hi_u32_b32 v1, s7, v1
	v_cmp_eq_u32_e32 vcc, 0, v1
	s_and_b64 s[10:11], exec, vcc
	s_mov_b64 exec, s[10:11]
	s_cbranch_execz .LBB0_5
	s_lshl_b32 s9, s8, 8
	s_bcnt1_i32_b64 s6, s[6:7]
	v_mov_b32_e32 v1, s9
	v_mov_b32_e32 v2, s6
	global_atomic_add v1, v2, s[2:3] offset:1024

.Lcodepf_end:
	.section	.rodata,"a",@progbits
	.p2align	6, 0x0
